# same bf16 peephole with a wider hazard-safety window around SGPR-writing VALU ops (16 extra s_nop in phase 0 only)
# baseline (speedup 1.0000x reference)
; DI unsigned pk2(float lo, float hi) { return f2bf(lo) | (f2bf(hi) << 16); }
; DI void lds_barrier() { asm volatile("s_waitcnt lgkmcnt(0)" ::: "memory"); __builtin_amdgcn_s_barrier(); asm volatile("" ::: "memory"); }
; DI void conv_T(const float* src, int K, int N, bf16_t* dst, int grp, int gstride, int goff, LAS float* tile) {
;     ...
;         lds_barrier();
;         {
;             const int nn = tid >> 3, k8 = (tid & 7) * 8, n = n0 + nn;
;             if (n < N) {
;                 float x[8];
; #pragma unroll
;                 for (int j = 0; j < 8; ++j) x[j] = tile[(k8 + j) * 65 + nn];
;                 u32x4 w; w.x = pk2(x[0], x[1]); w.y = pk2(x[2], x[3]); w.z = pk2(x[4], x[5]); w.w = pk2(x[6], x[7]);
;                 const size_t row = (size_t)(n / grp) * gstride + (n % grp) + goff;
;                 *(u32x4*)(dst + row * K + k0 + k8) = w;
;             }
.LBB0_101:
	s_ashr_i32 s2, s8, 31
	s_lshr_b32 s2, s2, 28
	s_add_i32 s2, s8, s2
	s_ashr_i32 s8, s2, 4
	s_waitcnt lgkmcnt(0)
	s_barrier
	v_add_u32_e32 v8, s6, v13
	s_lshl_b32 s2, s8, 10
	v_subrev_u32_e32 v8, s2, v8
	v_cmp_gt_i32_e32 vcc, s31, v8
	s_and_saveexec_b64 s[2:3], vcc
	s_cbranch_execz .LBB0_94
	ds_read2_b32 v[10:11], v16 offset1:65
	ds_read2_b32 v[20:21], v16 offset0:130 offset1:195
	v_add_u32_e32 v9, 0x400, v16
	ds_read2_b32 v[22:23], v9 offset0:4 offset1:69
	ds_read2_b32 v[24:25], v9 offset0:134 offset1:199
	v_readlane_b32 s10, v253, 26
	s_waitcnt lgkmcnt(3)
	s_nop 0
	s_nop 0
	s_nop 0
	s_nop 0
	s_nop 0
	v_cvt_pk_bf16_f32 v18, v10, v11
	s_waitcnt lgkmcnt(2)
	v_cvt_pk_bf16_f32 v19, v20, v21
	s_waitcnt lgkmcnt(1)
	v_cvt_pk_bf16_f32 v20, v22, v23
	s_waitcnt lgkmcnt(0)
	v_cvt_pk_bf16_f32 v9, v24, v24
	v_lshrrev_b32_e32 v9, 16, v9
	v_cvt_pk_bf16_f32 v10, v25, v25
	v_and_or_b32 v21, v10, s39, v9
	v_ashrrev_i32_e32 v9, 31, v8
	v_lshrrev_b32_e32 v9, 2, v9
	v_add_u32_e32 v9, v8, v9
	v_and_b32_e32 v9, -2.0, v9
	v_sub_u32_e32 v8, v8, v9
	v_ashrrev_i32_e32 v9, 31, v8
	s_lshl_b32 s8, s8, 6
	v_lshlrev_b64 v[8:9], 11, v[8:9]
	v_readlane_b32 s11, v253, 27
	s_ashr_i32 s9, s8, 31
	s_nop 0
	v_lshl_add_u64 v[8:9], s[10:11], 0, v[8:9]
	v_lshl_add_u64 v[8:9], s[8:9], 1, v[8:9]
	v_lshl_add_u64 v[8:9], v[8:9], 0, v[136:137]
	global_store_dwordx4 v[8:9], v[18:21], off
	s_branch .LBB0_94

; DI unsigned pk2(float lo, float hi) { return f2bf(lo) | (f2bf(hi) << 16); }
; DI void lds_barrier() { asm volatile("s_waitcnt lgkmcnt(0)" ::: "memory"); __builtin_amdgcn_s_barrier(); asm volatile("" ::: "memory"); }
; DI void conv_T(const float* src, int K, int N, bf16_t* dst, int grp, int gstride, int goff, LAS float* tile) {
;     ...
;         lds_barrier();
;         {
;             const int nn = tid >> 3, k8 = (tid & 7) * 8, n = n0 + nn;
;             if (n < N) {
;                 float x[8];
; #pragma unroll
;                 for (int j = 0; j < 8; ++j) x[j] = tile[(k8 + j) * 65 + nn];
;                 u32x4 w; w.x = pk2(x[0], x[1]); w.y = pk2(x[2], x[3]); w.z = pk2(x[4], x[5]); w.w = pk2(x[6], x[7]);
;                 const size_t row = (size_t)(n / grp) * gstride + (n % grp) + goff;
;                 *(u32x4*)(dst + row * K + k0 + k8) = w;
;             }
.LBB0_116:
	s_ashr_i32 s4, s10, 31
	s_lshr_b32 s4, s4, 28
	s_add_i32 s4, s10, s4
	s_ashr_i32 s10, s4, 4
	s_waitcnt lgkmcnt(0)
	s_barrier
	v_add_u32_e32 v8, s8, v13
	s_lshl_b32 s4, s10, 10
	v_subrev_u32_e32 v8, s4, v8
	v_cmp_gt_i32_e32 vcc, s31, v8
	s_and_saveexec_b64 s[4:5], vcc
	s_cbranch_execz .LBB0_109
	ds_read2_b32 v[10:11], v16 offset1:65
	ds_read2_b32 v[20:21], v16 offset0:130 offset1:195
	v_add_u32_e32 v9, 0x400, v16
	ds_read2_b32 v[22:23], v9 offset0:4 offset1:69
	ds_read2_b32 v[24:25], v9 offset0:134 offset1:199
	v_readlane_b32 s12, v253, 31
	s_waitcnt lgkmcnt(3)
	s_nop 0
	s_nop 0
	s_nop 0
	s_nop 0
	s_nop 0
	v_cvt_pk_bf16_f32 v18, v10, v11
	s_waitcnt lgkmcnt(2)
	v_cvt_pk_bf16_f32 v19, v20, v21
	s_waitcnt lgkmcnt(1)
	v_cvt_pk_bf16_f32 v20, v22, v23
	s_waitcnt lgkmcnt(0)
	v_cvt_pk_bf16_f32 v9, v24, v24
	v_lshrrev_b32_e32 v9, 16, v9
	v_cvt_pk_bf16_f32 v10, v25, v25
	v_and_or_b32 v21, v10, s39, v9
	v_ashrrev_i32_e32 v9, 31, v8
	v_lshrrev_b32_e32 v9, 2, v9
	v_add_u32_e32 v9, v8, v9
	v_and_b32_e32 v9, -2.0, v9
	v_sub_u32_e32 v8, v8, v9
	v_ashrrev_i32_e32 v9, 31, v8
	s_lshl_b32 s10, s10, 6
	v_lshlrev_b64 v[8:9], 9, v[8:9]
	v_readlane_b32 s13, v253, 32
	s_ashr_i32 s11, s10, 31
	s_nop 0
	v_lshl_add_u64 v[8:9], s[12:13], 0, v[8:9]
	v_lshl_add_u64 v[8:9], s[10:11], 1, v[8:9]
	v_lshl_add_u64 v[8:9], v[8:9], 0, v[136:137]
	global_store_dwordx4 v[8:9], v[18:21], off
	s_branch .LBB0_109

; DI unsigned pk2(float lo, float hi) { return f2bf(lo) | (f2bf(hi) << 16); }
; DI void lds_barrier() { asm volatile("s_waitcnt lgkmcnt(0)" ::: "memory"); __builtin_amdgcn_s_barrier(); asm volatile("" ::: "memory"); }
; DI void conv_T(const float* src, int K, int N, bf16_t* dst, int grp, int gstride, int goff, LAS float* tile) {
;     ...
;         lds_barrier();
;         {
;             const int nn = tid >> 3, k8 = (tid & 7) * 8, n = n0 + nn;
;             if (n < N) {
;                 float x[8];
; #pragma unroll
;                 for (int j = 0; j < 8; ++j) x[j] = tile[(k8 + j) * 65 + nn];
;                 u32x4 w; w.x = pk2(x[0], x[1]); w.y = pk2(x[2], x[3]); w.z = pk2(x[4], x[5]); w.w = pk2(x[6], x[7]);
;                 const size_t row = (size_t)(n / grp) * gstride + (n % grp) + goff;
;                 *(u32x4*)(dst + row * K + k0 + k8) = w;
;             }
.LBB0_131:
	s_ashr_i32 s6, s12, 31
	s_lshr_b32 s6, s6, 28
	s_add_i32 s6, s12, s6
	s_ashr_i32 s12, s6, 4
	s_waitcnt lgkmcnt(0)
	s_barrier
	v_add_u32_e32 v8, s10, v13
	s_lshl_b32 s6, s12, 10
	v_subrev_u32_e32 v8, s6, v8
	v_cmp_gt_i32_e32 vcc, s31, v8
	s_and_saveexec_b64 s[6:7], vcc
	s_cbranch_execz .LBB0_124
	ds_read2_b32 v[10:11], v16 offset1:65
	ds_read2_b32 v[20:21], v16 offset0:130 offset1:195
	v_add_u32_e32 v9, 0x400, v16
	ds_read2_b32 v[22:23], v9 offset0:4 offset1:69
	ds_read2_b32 v[24:25], v9 offset0:134 offset1:199
	v_readlane_b32 s14, v253, 33
	s_waitcnt lgkmcnt(3)
	s_nop 0
	s_nop 0
	s_nop 0
	s_nop 0
	s_nop 0
	v_cvt_pk_bf16_f32 v18, v10, v11
	s_waitcnt lgkmcnt(2)
	v_cvt_pk_bf16_f32 v19, v20, v21
	s_waitcnt lgkmcnt(1)
	v_cvt_pk_bf16_f32 v20, v22, v23
	s_waitcnt lgkmcnt(0)
	v_cvt_pk_bf16_f32 v9, v24, v24
	v_lshrrev_b32_e32 v9, 16, v9
	v_cvt_pk_bf16_f32 v10, v25, v25
	v_and_or_b32 v21, v10, s39, v9
	v_ashrrev_i32_e32 v9, 31, v8
	v_lshrrev_b32_e32 v9, 2, v9
	v_add_u32_e32 v9, v8, v9
	v_and_b32_e32 v9, -2.0, v9
	v_sub_u32_e32 v8, v8, v9
	v_ashrrev_i32_e32 v9, 31, v8
	s_lshl_b32 s12, s12, 6
	v_lshlrev_b64 v[8:9], 11, v[8:9]
	v_readlane_b32 s15, v253, 34
	s_ashr_i32 s13, s12, 31
	s_nop 0
	v_lshl_add_u64 v[8:9], s[14:15], 0, v[8:9]
	v_lshl_add_u64 v[8:9], s[12:13], 1, v[8:9]
	v_lshl_add_u64 v[8:9], v[8:9], 0, v[136:137]
	global_store_dwordx4 v[8:9], v[18:21], off
	s_branch .LBB0_124

; DI unsigned pk2(float lo, float hi) { return f2bf(lo) | (f2bf(hi) << 16); }
; DI void lds_barrier() { asm volatile("s_waitcnt lgkmcnt(0)" ::: "memory"); __builtin_amdgcn_s_barrier(); asm volatile("" ::: "memory"); }
; DI void conv_T(const float* src, int K, int N, bf16_t* dst, int grp, int gstride, int goff, LAS float* tile) {
;     ...
;         lds_barrier();
;         {
;             const int nn = tid >> 3, k8 = (tid & 7) * 8, n = n0 + nn;
;             if (n < N) {
;                 float x[8];
; #pragma unroll
;                 for (int j = 0; j < 8; ++j) x[j] = tile[(k8 + j) * 65 + nn];
;                 u32x4 w; w.x = pk2(x[0], x[1]); w.y = pk2(x[2], x[3]); w.z = pk2(x[4], x[5]); w.w = pk2(x[6], x[7]);
;                 const size_t row = (size_t)(n / grp) * gstride + (n % grp) + goff;
;                 *(u32x4*)(dst + row * K + k0 + k8) = w;
;             }
.LBB0_146:
	s_ashr_i32 s4, s10, 31
	s_lshr_b32 s4, s4, 28
	s_add_i32 s4, s10, s4
	s_ashr_i32 s10, s4, 4
	s_waitcnt lgkmcnt(0)
	s_barrier
	v_add_u32_e32 v8, s8, v13
	s_lshl_b32 s4, s10, 10
	v_subrev_u32_e32 v8, s4, v8
	v_cmp_gt_i32_e32 vcc, s31, v8
	s_and_saveexec_b64 s[4:5], vcc
	s_cbranch_execz .LBB0_139
	ds_read2_b32 v[10:11], v16 offset1:65
	ds_read2_b32 v[20:21], v16 offset0:130 offset1:195
	v_add_u32_e32 v9, 0x400, v16
	ds_read2_b32 v[22:23], v9 offset0:4 offset1:69
	ds_read2_b32 v[24:25], v9 offset0:134 offset1:199
	v_readlane_b32 s12, v253, 35
	s_waitcnt lgkmcnt(3)
	s_nop 0
	s_nop 0
	s_nop 0
	s_nop 0
	s_nop 0
	v_cvt_pk_bf16_f32 v18, v10, v11
	s_waitcnt lgkmcnt(2)
	v_cvt_pk_bf16_f32 v19, v20, v21
	s_waitcnt lgkmcnt(1)
	v_cvt_pk_bf16_f32 v20, v22, v23
	s_waitcnt lgkmcnt(0)
	v_cvt_pk_bf16_f32 v9, v24, v24
	v_lshrrev_b32_e32 v9, 16, v9
	v_cvt_pk_bf16_f32 v10, v25, v25
	v_and_or_b32 v21, v10, s39, v9
	v_ashrrev_i32_e32 v9, 31, v8
	v_lshrrev_b32_e32 v9, 2, v9
	v_add_u32_e32 v9, v8, v9
	v_and_b32_e32 v9, -2.0, v9
	v_sub_u32_e32 v8, v8, v9
	v_ashrrev_i32_e32 v9, 31, v8
	s_lshl_b32 s10, s10, 6
	v_lshlrev_b64 v[8:9], 9, v[8:9]
	v_readlane_b32 s13, v253, 36
	s_ashr_i32 s11, s10, 31
	s_nop 0
	v_lshl_add_u64 v[8:9], s[12:13], 0, v[8:9]
	v_lshl_add_u64 v[8:9], s[10:11], 1, v[8:9]
	v_lshl_add_u64 v[8:9], v[8:9], 0, v[136:137]
	global_store_dwordx4 v[8:9], v[18:21], off
	s_branch .LBB0_139

; DI unsigned pk2(float lo, float hi) { return f2bf(lo) | (f2bf(hi) << 16); }
; DI void lds_barrier() { asm volatile("s_waitcnt lgkmcnt(0)" ::: "memory"); __builtin_amdgcn_s_barrier(); asm volatile("" ::: "memory"); }
; DI void conv_T(const float* src, int K, int N, bf16_t* dst, int grp, int gstride, int goff, LAS float* tile) {
;     ...
;         lds_barrier();
;         {
;             const int nn = tid >> 3, k8 = (tid & 7) * 8, n = n0 + nn;
;             if (n < N) {
;                 float x[8];
; #pragma unroll
;                 for (int j = 0; j < 8; ++j) x[j] = tile[(k8 + j) * 65 + nn];
;                 u32x4 w; w.x = pk2(x[0], x[1]); w.y = pk2(x[2], x[3]); w.z = pk2(x[4], x[5]); w.w = pk2(x[6], x[7]);
;                 const size_t row = (size_t)(n / grp) * gstride + (n % grp) + goff;
;                 *(u32x4*)(dst + row * K + k0 + k8) = w;
;             }
.LBB0_161:
	s_mul_hi_i32 s4, s10, 0x92492493
	s_add_i32 s4, s4, s10
	s_lshr_b32 s5, s4, 31
	s_ashr_i32 s10, s4, 4
	s_add_i32 s10, s10, s5
	s_mul_i32 s4, s10, 0xfffff900
	s_waitcnt lgkmcnt(0)
	s_barrier
	s_add_i32 s4, s4, s8
	v_add_u32_e32 v8, s4, v11
	s_movk_i32 s4, 0x700
	v_cmp_gt_i32_e32 vcc, s4, v8
	s_and_saveexec_b64 s[4:5], vcc
	s_cbranch_execz .LBB0_154
	ds_read2_b32 v[16:17], v14 offset1:65
	ds_read2_b32 v[18:19], v14 offset0:130 offset1:195
	v_add_u32_e32 v9, 0x400, v14
	ds_read2_b32 v[20:21], v9 offset0:4 offset1:69
	ds_read2_b32 v[22:23], v9 offset0:134 offset1:199
	v_readlane_b32 s12, v253, 57
	s_waitcnt lgkmcnt(3)
	s_nop 0
	s_nop 0
	s_nop 0
	s_nop 0
	s_nop 0
	v_cvt_pk_bf16_f32 v16, v16, v17
	s_waitcnt lgkmcnt(2)
	v_cvt_pk_bf16_f32 v17, v18, v19
	s_waitcnt lgkmcnt(1)
	v_cvt_pk_bf16_f32 v18, v20, v21
	s_waitcnt lgkmcnt(0)
	v_cvt_pk_bf16_f32 v9, v22, v22
	v_lshrrev_b32_e32 v9, 16, v9
	v_cvt_pk_bf16_f32 v15, v23, v23
	v_and_or_b32 v19, v15, s39, v9
	v_ashrrev_i32_e32 v9, 31, v8
	v_lshrrev_b32_e32 v9, 2, v9
	v_add_u32_e32 v9, v8, v9
	v_and_b32_e32 v9, -2.0, v9
	v_sub_u32_e32 v8, v8, v9
	v_ashrrev_i32_e32 v9, 31, v8
	s_lshl_b32 s10, s10, 6
	v_lshlrev_b64 v[8:9], 11, v[8:9]
	v_readlane_b32 s13, v253, 58
	s_ashr_i32 s11, s10, 31
	s_nop 0
	v_lshl_add_u64 v[8:9], s[12:13], 0, v[8:9]
	v_lshl_add_u64 v[8:9], s[10:11], 1, v[8:9]
	v_lshl_add_u64 v[8:9], v[8:9], 0, v[136:137]
	global_store_dwordx4 v[8:9], v[16:19], off
	s_branch .LBB0_154

; DI unsigned pk2(float lo, float hi) { return f2bf(lo) | (f2bf(hi) << 16); }
; DI void lds_barrier() { asm volatile("s_waitcnt lgkmcnt(0)" ::: "memory"); __builtin_amdgcn_s_barrier(); asm volatile("" ::: "memory"); }
; DI void conv_T(const float* src, int K, int N, bf16_t* dst, int grp, int gstride, int goff, LAS float* tile) {
;     ...
;         lds_barrier();
;         {
;             const int nn = tid >> 3, k8 = (tid & 7) * 8, n = n0 + nn;
;             if (n < N) {
;                 float x[8];
; #pragma unroll
;                 for (int j = 0; j < 8; ++j) x[j] = tile[(k8 + j) * 65 + nn];
;                 u32x4 w; w.x = pk2(x[0], x[1]); w.y = pk2(x[2], x[3]); w.z = pk2(x[4], x[5]); w.w = pk2(x[6], x[7]);
;                 const size_t row = (size_t)(n / grp) * gstride + (n % grp) + goff;
;                 *(u32x4*)(dst + row * K + k0 + k8) = w;
;             }
.LBB0_176:
	s_ashr_i32 s2, s8, 31
	s_lshr_b32 s2, s2, 28
	s_add_i32 s2, s8, s2
	s_ashr_i32 s8, s2, 4
	s_waitcnt lgkmcnt(0)
	s_barrier
	v_add_u32_e32 v8, s6, v13
	s_lshl_b32 s2, s8, 10
	v_subrev_u32_e32 v8, s2, v8
	v_cmp_gt_i32_e32 vcc, s31, v8
	s_and_saveexec_b64 s[2:3], vcc
	s_cbranch_execz .LBB0_169
	ds_read2_b32 v[10:11], v16 offset1:65
	ds_read2_b32 v[20:21], v16 offset0:130 offset1:195
	v_add_u32_e32 v9, 0x400, v16
	ds_read2_b32 v[22:23], v9 offset0:4 offset1:69
	ds_read2_b32 v[24:25], v9 offset0:134 offset1:199
	v_readlane_b32 s10, v253, 63
	s_waitcnt lgkmcnt(3)
	s_nop 0
	s_nop 0
	s_nop 0
	s_nop 0
	s_nop 0
	v_cvt_pk_bf16_f32 v18, v10, v11
	s_waitcnt lgkmcnt(2)
	v_cvt_pk_bf16_f32 v19, v20, v21
	s_waitcnt lgkmcnt(1)
	v_cvt_pk_bf16_f32 v20, v22, v23
	s_waitcnt lgkmcnt(0)
	v_cvt_pk_bf16_f32 v9, v24, v24
	v_lshrrev_b32_e32 v9, 16, v9
	v_cvt_pk_bf16_f32 v10, v25, v25
	v_and_or_b32 v21, v10, s39, v9
	v_ashrrev_i32_e32 v9, 31, v8
	v_lshrrev_b32_e32 v9, 2, v9
	v_add_u32_e32 v9, v8, v9
	v_and_b32_e32 v9, -2.0, v9
	v_sub_u32_e32 v8, v8, v9
	v_ashrrev_i32_e32 v9, 31, v8
	s_lshl_b32 s8, s8, 6
	v_lshlrev_b64 v[8:9], 11, v[8:9]
	v_readlane_b32 s11, v254, 0
	s_ashr_i32 s9, s8, 31
	s_nop 0
	v_lshl_add_u64 v[8:9], s[10:11], 0, v[8:9]
	v_lshl_add_u64 v[8:9], s[8:9], 1, v[8:9]
	v_lshl_add_u64 v[8:9], v[8:9], 0, v[136:137]
	global_store_dwordx4 v[8:9], v[18:21], off
	s_branch .LBB0_169

; DI unsigned pk2(float lo, float hi) { return f2bf(lo) | (f2bf(hi) << 16); }
; DI void lds_barrier() { asm volatile("s_waitcnt lgkmcnt(0)" ::: "memory"); __builtin_amdgcn_s_barrier(); asm volatile("" ::: "memory"); }
; DI void conv_T(const float* src, int K, int N, bf16_t* dst, int grp, int gstride, int goff, LAS float* tile) {
;     ...
;         lds_barrier();
;         {
;             const int nn = tid >> 3, k8 = (tid & 7) * 8, n = n0 + nn;
;             if (n < N) {
;                 float x[8];
; #pragma unroll
;                 for (int j = 0; j < 8; ++j) x[j] = tile[(k8 + j) * 65 + nn];
;                 u32x4 w; w.x = pk2(x[0], x[1]); w.y = pk2(x[2], x[3]); w.z = pk2(x[4], x[5]); w.w = pk2(x[6], x[7]);
;                 const size_t row = (size_t)(n / grp) * gstride + (n % grp) + goff;
;                 *(u32x4*)(dst + row * K + k0 + k8) = w;
;             }
.LBB0_191:
	s_mul_hi_i32 s2, s8, 0x7e07e07f
	s_lshr_b32 s3, s2, 31
	s_ashr_i32 s8, s2, 5
	s_add_i32 s8, s8, s3
	s_mul_i32 s2, s8, 0xffffefc0
	s_waitcnt lgkmcnt(0)
	s_barrier
	s_add_i32 s2, s2, s6
	v_add_u32_e32 v8, s2, v11
	s_movk_i32 s2, 0x1010
	v_cmp_gt_i32_e32 vcc, s2, v8
	s_and_saveexec_b64 s[2:3], vcc
	s_cbranch_execz .LBB0_184
	ds_read2_b32 v[16:17], v14 offset1:65
	ds_read2_b32 v[18:19], v14 offset0:130 offset1:195
	v_add_u32_e32 v9, 0x400, v14
	ds_read2_b32 v[20:21], v9 offset0:4 offset1:69
	ds_read2_b32 v[22:23], v9 offset0:134 offset1:199
	v_readlane_b32 s10, v254, 1
	s_waitcnt lgkmcnt(3)
	s_nop 0
	s_nop 0
	s_nop 0
	s_nop 0
	s_nop 0
	v_cvt_pk_bf16_f32 v16, v16, v17
	s_waitcnt lgkmcnt(2)
	v_cvt_pk_bf16_f32 v17, v18, v19
	s_waitcnt lgkmcnt(1)
	v_cvt_pk_bf16_f32 v18, v20, v21
	s_waitcnt lgkmcnt(0)
	v_cvt_pk_bf16_f32 v9, v22, v22
	v_lshrrev_b32_e32 v9, 16, v9
	v_cvt_pk_bf16_f32 v15, v23, v23
	v_and_or_b32 v19, v15, s39, v9
	v_ashrrev_i32_e32 v9, 31, v8
	v_lshrrev_b32_e32 v9, 2, v9
	v_add_u32_e32 v9, v8, v9
	v_and_b32_e32 v9, -2.0, v9
	v_sub_u32_e32 v8, v8, v9
	v_ashrrev_i32_e32 v9, 31, v8
	s_lshl_b32 s8, s8, 6
	v_lshlrev_b64 v[8:9], 11, v[8:9]
	v_readlane_b32 s11, v254, 2
	s_ashr_i32 s9, s8, 31
	s_nop 0
	v_lshl_add_u64 v[8:9], s[10:11], 0, v[8:9]
	v_lshl_add_u64 v[8:9], s[8:9], 1, v[8:9]
	v_lshl_add_u64 v[8:9], v[8:9], 0, v[136:137]
	global_store_dwordx4 v[8:9], v[16:19], off
	s_branch .LBB0_184

; DI unsigned pk2(float lo, float hi) { return f2bf(lo) | (f2bf(hi) << 16); }
; DI void lds_barrier() { asm volatile("s_waitcnt lgkmcnt(0)" ::: "memory"); __builtin_amdgcn_s_barrier(); asm volatile("" ::: "memory"); }
; DI void conv_T(const float* src, int K, int N, bf16_t* dst, int grp, int gstride, int goff, LAS float* tile) {
;     ...
;         lds_barrier();
;         {
;             const int nn = tid >> 3, k8 = (tid & 7) * 8, n = n0 + nn;
;             if (n < N) {
;                 float x[8];
; #pragma unroll
;                 for (int j = 0; j < 8; ++j) x[j] = tile[(k8 + j) * 65 + nn];
;                 u32x4 w; w.x = pk2(x[0], x[1]); w.y = pk2(x[2], x[3]); w.z = pk2(x[4], x[5]); w.w = pk2(x[6], x[7]);
;                 const size_t row = (size_t)(n / grp) * gstride + (n % grp) + goff;
;                 *(u32x4*)(dst + row * K + k0 + k8) = w;
;             }
.LBB0_206:
	s_ashr_i32 s2, s8, 31
	s_lshr_b32 s2, s2, 28
	s_add_i32 s2, s8, s2
	s_ashr_i32 s8, s2, 4
	s_waitcnt lgkmcnt(0)
	s_barrier
	v_add_u32_e32 v8, s6, v13
	s_lshl_b32 s2, s8, 10
	v_subrev_u32_e32 v8, s2, v8
	v_cmp_gt_i32_e32 vcc, s31, v8
	s_and_saveexec_b64 s[2:3], vcc
	s_cbranch_execz .LBB0_199
	ds_read2_b32 v[10:11], v16 offset1:65
	ds_read2_b32 v[20:21], v16 offset0:130 offset1:195
	v_add_u32_e32 v9, 0x400, v16
	ds_read2_b32 v[22:23], v9 offset0:4 offset1:69
	ds_read2_b32 v[24:25], v9 offset0:134 offset1:199
	v_readlane_b32 s10, v254, 7
	s_waitcnt lgkmcnt(3)
	s_nop 0
	s_nop 0
	s_nop 0
	s_nop 0
	s_nop 0
	v_cvt_pk_bf16_f32 v18, v10, v11
	s_waitcnt lgkmcnt(2)
	v_cvt_pk_bf16_f32 v19, v20, v21
	s_waitcnt lgkmcnt(1)
	v_cvt_pk_bf16_f32 v20, v22, v23
	s_waitcnt lgkmcnt(0)
	v_cvt_pk_bf16_f32 v9, v24, v24
	v_lshrrev_b32_e32 v9, 16, v9
	v_cvt_pk_bf16_f32 v10, v25, v25
	v_and_or_b32 v21, v10, s39, v9
	v_ashrrev_i32_e32 v9, 31, v8
	v_lshrrev_b32_e32 v9, 2, v9
	v_add_u32_e32 v9, v8, v9
	v_and_b32_e32 v9, -2.0, v9
	v_sub_u32_e32 v8, v8, v9
	v_ashrrev_i32_e32 v9, 31, v8
	s_lshl_b32 s8, s8, 6
	v_lshlrev_b64 v[8:9], 11, v[8:9]
	v_readlane_b32 s11, v254, 8
	s_ashr_i32 s9, s8, 31
	s_nop 0
	v_lshl_add_u64 v[8:9], s[10:11], 0, v[8:9]
	v_lshl_add_u64 v[8:9], s[8:9], 1, v[8:9]
	v_lshl_add_u64 v[8:9], v[8:9], 0, v[136:137]
	global_store_dwordx4 v[8:9], v[18:21], off
	s_branch .LBB0_199
